# saddr LDS-DMA loads in the in-projection and output-projection GEMM K-loops only
# baseline (speedup 1.0000x reference)
; #define PG8_STAGE(bufoff, gbase, voff) do { _Pragma("unroll") for (int _i = 0; _i < 2; ++_i) \
;         __builtin_amdgcn_global_load_lds((const unsigned*)((const char*)(gbase) + (voff)[_i]), (LAS unsigned*)(lds + (bufoff) + ldsw + _i * 8192), 16, 0, 0); } while (0)
; #define PG8_LDA(dst, b, h) do { _Pragma("unroll") for (int m = 0; m < 4; ++m) _Pragma("unroll") for (int k = 0; k < 2; ++k) dst[m][k] = *(const LAS bf16x8*)(lds + PG8_SA(b, h) + aoff + m * 2048 + k * 1024); } while (0)
; #define PG8_WAIT_V(n) asm volatile("s_waitcnt vmcnt(" #n ")" ::: "memory")
; template <class Epi, class Sched, bool ALIGN_EPI = false, bool SP2 = false, bool TWOA = false, bool AGM = false>
; __device__ __forceinline__ void gemm_phase(LAS unsigned char* lds, const Gemm g, const Sched& S, const Epi& E, int wid) {
;     ...
;         const bool has_next = S.next(ui + 1, nxt);
;         const char* nA = has_next ? (const char*)g.A + (size_t)nxt.pm * tstepA : cA; const char* nB = has_next ? (const char*)g.Bt + (size_t)nxt.pn * tstep : cB;
;         for (int t = 0; t < nt; t += 2) {
;             const bool last = (t == nt - 2);
;             const char* cA2 = TWOA ? (const char*)g.A2 + (cA - (const char*)g.A) - (size_t)nh * kstepA : cA;
;             const char* a1_ = (TWOA && t + 1 >= nh ? cA2 : cA) + (size_t)(t + 1) * kstepA;
;             const char* a2_ = last ? nA : (TWOA && t + 2 >= nh ? cA2 : cA) + (size_t)(t + 2) * kstepA; const char* a1 = a1_; const char* a2 = a2_; const char* b2 = last ? nB : cB + (size_t)(t + 2) * kstep;
;             if constexpr (TWOA) { asm volatile("" : "+s"(a1)); asm volatile("" : "+s"(a2)); }
;             const char* a3 = a2 + kstepA; const char* b3 = b2 + kstep;
;             if (last && has_next) S.a_ready(nxt);
;             if constexpr (has_mid<Epi>::value) { if (t == nh) E.mid(acc, cur, wr, wc, fr, fq); }
;             if constexpr (SP2) {
;             PG8_LDB(B0, 0, 0); PG8_LDB(B1, 0, 1); PG8_SCHED; PG8_LDA(At, 0, 0); PG8_STAGE(PG8_SA(1, 1), a1 + hstepA, voffA);
;             PG8_WAIT_V(8); PG8_WAIT_L(0); PG8_BAR; PG8_MMA(0, 0, At, B0); PG8_MMA(0, 1, At, B1); PG8_BAR; PG8_SCHED;
;             PG8_LDA(At, 0, 1); PG8_STAGE(PG8_SB(0, 0), b2, voffB); PG8_STAGE(PG8_SB(0, 1), b2 + hstep, voffB); PG8_STAGE(PG8_SA(0, 0), a2, voffA);
;             PG8_WAIT_V(8); PG8_WAIT_L(0); PG8_BAR; PG8_MMA(1, 0, At, B0); PG8_MMA(1, 1, At, B1); PG8_BAR; PG8_SCHED;
.LBB0_901:
	ds_read_b128 v[146:149], v155
	ds_read_b128 v[158:161], v155 offset:1024
	ds_read_b128 v[162:165], v155 offset:2048
	ds_read_b128 v[166:169], v155 offset:3072
	ds_read_b128 v[170:173], v156
	ds_read_b128 v[174:177], v156 offset:1024
	ds_read_b128 v[178:181], v156 offset:2048
	ds_read_b128 v[182:185], v156 offset:3072
	s_add_u32 s38, s36, 0xfff00080
	s_addc_u32 s39, s37, -1
	s_cmp_eq_u32 s67, 60
	s_cselect_b32 s41, s27, s39
	s_cselect_b32 s40, s63, s38
	s_cselect_b32 s39, s25, s66
	s_cselect_b32 s38, s64, s65
	s_add_i32 m0, s35, 0xc000
	ds_read_b128 v[186:189], v157
	ds_read_b128 v[190:193], v157 offset:1024
	ds_read_b128 v[194:197], v157 offset:2048
	ds_read_b128 v[198:201], v157 offset:3072
	ds_read_b128 v[202:205], v157 offset:4096
	ds_read_b128 v[206:209], v157 offset:5120
	ds_read_b128 v[210:213], v157 offset:6144
	ds_read_b128 v[214:217], v157 offset:7168
	global_load_lds_dwordx4 v138, s[36:37]
	s_add_i32 m0, s35, 0xe000
	s_nop 0
	global_load_lds_dwordx4 v140, s[36:37]
	s_waitcnt vmcnt(8)
	s_waitcnt lgkmcnt(0)
	s_barrier
	s_setprio 1
	s_waitcnt lgkmcnt(0)
	v_mfma_f32_16x16x32_bf16 v[124:127], v[146:149], v[186:189], v[124:127]
	v_mfma_f32_16x16x32_bf16 v[120:123], v[162:165], v[186:189], v[120:123]
	v_mfma_f32_16x16x32_bf16 v[116:119], v[146:149], v[194:197], v[116:119]
	v_mfma_f32_16x16x32_bf16 v[108:111], v[162:165], v[194:197], v[108:111]
	v_mfma_f32_16x16x32_bf16 v[100:103], v[146:149], v[202:205], v[100:103]
	v_mfma_f32_16x16x32_bf16 v[92:95], v[162:165], v[202:205], v[92:95]
	v_mfma_f32_16x16x32_bf16 v[84:87], v[146:149], v[210:213], v[84:87]
	v_mfma_f32_16x16x32_bf16 v[76:79], v[162:165], v[210:213], v[76:79]
	v_mfma_f32_16x16x32_bf16 v[124:127], v[158:161], v[190:193], v[124:127]
	v_mfma_f32_16x16x32_bf16 v[120:123], v[166:169], v[190:193], v[120:123]
	v_mfma_f32_16x16x32_bf16 v[116:119], v[158:161], v[198:201], v[116:119]
	v_mfma_f32_16x16x32_bf16 v[108:111], v[166:169], v[198:201], v[108:111]
	v_mfma_f32_16x16x32_bf16 v[100:103], v[158:161], v[206:209], v[100:103]
	v_mfma_f32_16x16x32_bf16 v[92:95], v[166:169], v[206:209], v[92:95]
	v_mfma_f32_16x16x32_bf16 v[84:87], v[158:161], v[214:217], v[84:87]
	v_mfma_f32_16x16x32_bf16 v[76:79], v[166:169], v[214:217], v[76:79]
	s_setprio 0
	s_setprio 1
	v_mfma_f32_16x16x32_bf16 v[112:115], v[170:173], v[186:189], v[112:115]
	v_mfma_f32_16x16x32_bf16 v[104:107], v[178:181], v[186:189], v[104:107]
	v_mfma_f32_16x16x32_bf16 v[96:99], v[170:173], v[194:197], v[96:99]
	v_mfma_f32_16x16x32_bf16 v[88:91], v[178:181], v[194:197], v[88:91]
	v_mfma_f32_16x16x32_bf16 v[80:83], v[170:173], v[202:205], v[80:83]
	v_mfma_f32_16x16x32_bf16 v[72:75], v[178:181], v[202:205], v[72:75]
	v_mfma_f32_16x16x32_bf16 v[68:71], v[170:173], v[210:213], v[68:71]
	v_mfma_f32_16x16x32_bf16 v[64:67], v[178:181], v[210:213], v[64:67]
	v_mfma_f32_16x16x32_bf16 v[112:115], v[174:177], v[190:193], v[112:115]
	v_mfma_f32_16x16x32_bf16 v[104:107], v[182:185], v[190:193], v[104:107]
	v_mfma_f32_16x16x32_bf16 v[96:99], v[174:177], v[198:201], v[96:99]
	v_mfma_f32_16x16x32_bf16 v[88:91], v[182:185], v[198:201], v[88:91]
	v_mfma_f32_16x16x32_bf16 v[80:83], v[174:177], v[206:209], v[80:83]
	v_mfma_f32_16x16x32_bf16 v[72:75], v[182:185], v[206:209], v[72:75]
	v_mfma_f32_16x16x32_bf16 v[68:71], v[174:177], v[214:217], v[68:71]
	v_mfma_f32_16x16x32_bf16 v[64:67], v[182:185], v[214:217], v[64:67]
	s_setprio 0
	s_barrier
	s_add_i32 s68, s54, s44
	s_add_u32 s98, s38, s6
	s_addc_u32 s99, s39, s7
	s_mov_b32 m0, s68
	ds_read_b128 v[186:189], v157 offset:16384
	ds_read_b128 v[190:193], v157 offset:17408
	ds_read_b128 v[194:197], v157 offset:18432
	ds_read_b128 v[198:201], v157 offset:19456
	ds_read_b128 v[202:205], v157 offset:20480
	ds_read_b128 v[206:209], v157 offset:21504
	ds_read_b128 v[210:213], v157 offset:22528
	ds_read_b128 v[214:217], v157 offset:23552
	global_load_lds_dwordx4 v132, s[38:39]
	s_add_i32 m0, s68, 0x2000
	s_add_u32 s68, s38, 0x100000
	s_addc_u32 s69, s39, 0
	s_add_i32 s70, s55, s44
	global_load_lds_dwordx4 v128, s[38:39]
	s_mov_b32 m0, s70
	s_nop 0
	global_load_lds_dwordx4 v132, s[68:69]
	s_add_i32 m0, s70, 0x2000
	s_nop 0
	global_load_lds_dwordx4 v128, s[68:69]
	s_add_u32 s100, s40, s6
	s_addc_u32 s101, s41, s7
	s_mov_b32 m0, s35
	s_nop 0
	global_load_lds_dwordx4 v134, s[40:41]
	s_mov_b32 m0, s47
	s_nop 0
	global_load_lds_dwordx4 v130, s[40:41]
	s_waitcnt vmcnt(8)
	s_waitcnt lgkmcnt(0)
	s_barrier
	s_setprio 1
	s_waitcnt lgkmcnt(0)
	v_mfma_f32_16x16x32_bf16 v[60:63], v[146:149], v[186:189], v[60:63]
	v_mfma_f32_16x16x32_bf16 v[56:59], v[162:165], v[186:189], v[56:59]
	v_mfma_f32_16x16x32_bf16 v[52:55], v[146:149], v[194:197], v[52:55]
	v_mfma_f32_16x16x32_bf16 v[44:47], v[162:165], v[194:197], v[44:47]
	v_mfma_f32_16x16x32_bf16 v[36:39], v[146:149], v[202:205], v[36:39]
	v_mfma_f32_16x16x32_bf16 v[28:31], v[162:165], v[202:205], v[28:31]
	v_mfma_f32_16x16x32_bf16 v[20:23], v[146:149], v[210:213], v[20:23]
	v_mfma_f32_16x16x32_bf16 v[12:15], v[162:165], v[210:213], v[12:15]
	v_mfma_f32_16x16x32_bf16 v[60:63], v[158:161], v[190:193], v[60:63]
	v_mfma_f32_16x16x32_bf16 v[56:59], v[166:169], v[190:193], v[56:59]
	v_mfma_f32_16x16x32_bf16 v[52:55], v[158:161], v[198:201], v[52:55]
	v_mfma_f32_16x16x32_bf16 v[44:47], v[166:169], v[198:201], v[44:47]
	v_mfma_f32_16x16x32_bf16 v[36:39], v[158:161], v[206:209], v[36:39]
	v_mfma_f32_16x16x32_bf16 v[28:31], v[166:169], v[206:209], v[28:31]
	v_mfma_f32_16x16x32_bf16 v[20:23], v[158:161], v[214:217], v[20:23]
	v_mfma_f32_16x16x32_bf16 v[12:15], v[166:169], v[214:217], v[12:15]
	s_setprio 0
	s_setprio 1
	v_mfma_f32_16x16x32_bf16 v[48:51], v[170:173], v[186:189], v[48:51]
	v_mfma_f32_16x16x32_bf16 v[40:43], v[178:181], v[186:189], v[40:43]
	v_mfma_f32_16x16x32_bf16 v[32:35], v[170:173], v[194:197], v[32:35]
	v_mfma_f32_16x16x32_bf16 v[24:27], v[178:181], v[194:197], v[24:27]
	v_mfma_f32_16x16x32_bf16 v[16:19], v[170:173], v[202:205], v[16:19]
	v_mfma_f32_16x16x32_bf16 v[8:11], v[178:181], v[202:205], v[8:11]
	v_mfma_f32_16x16x32_bf16 v[4:7], v[170:173], v[210:213], v[4:7]
	v_mfma_f32_16x16x32_bf16 v[0:3], v[178:181], v[210:213], v[0:3]
	v_mfma_f32_16x16x32_bf16 v[48:51], v[174:177], v[190:193], v[48:51]
	v_mfma_f32_16x16x32_bf16 v[40:43], v[182:185], v[190:193], v[40:43]
	v_mfma_f32_16x16x32_bf16 v[32:35], v[174:177], v[198:201], v[32:35]
	v_mfma_f32_16x16x32_bf16 v[24:27], v[182:185], v[198:201], v[24:27]
	v_mfma_f32_16x16x32_bf16 v[16:19], v[174:177], v[206:209], v[16:19]
	v_mfma_f32_16x16x32_bf16 v[8:11], v[182:185], v[206:209], v[8:11]
	v_mfma_f32_16x16x32_bf16 v[4:7], v[174:177], v[214:217], v[4:7]
	v_mfma_f32_16x16x32_bf16 v[0:3], v[182:185], v[214:217], v[0:3]
	s_setprio 0
	s_barrier
; #define PG8_STAGE(bufoff, gbase, voff) do { _Pragma("unroll") for (int _i = 0; _i < 2; ++_i) \
;         __builtin_amdgcn_global_load_lds((const unsigned*)((const char*)(gbase) + (voff)[_i]), (LAS unsigned*)(lds + (bufoff) + ldsw + _i * 8192), 16, 0, 0); } while (0)
; #define PG8_LDA(dst, b, h) do { _Pragma("unroll") for (int m = 0; m < 4; ++m) _Pragma("unroll") for (int k = 0; k < 2; ++k) dst[m][k] = *(const LAS bf16x8*)(lds + PG8_SA(b, h) + aoff + m * 2048 + k * 1024); } while (0)
; #define PG8_LDB(dst, b, h) do { _Pragma("unroll") for (int n = 0; n < 2; ++n) _Pragma("unroll") for (int k = 0; k < 2; ++k) dst[n][k] = *(const LAS bf16x8*)(lds + PG8_SB(b, h) + boff + n * 2048 + k * 1024); } while (0)
; #define PG8_MMA(ai, bj, At, Bt) do { __builtin_amdgcn_s_setprio(1); _Pragma("unroll") for (int m = 0; m < 4; ++m) _Pragma("unroll") for (int n = 0; n < 2; ++n) _Pragma("unroll") for (int k = 0; k < 2; ++k) \
;         acc[ai][bj][m][n] = __builtin_amdgcn_mfma_f32_16x16x32_bf16(Bt[n][k], At[m][k], acc[ai][bj][m][n], 0, 0, 0); __builtin_amdgcn_s_setprio(0); } while (0)
; #define PG8_WAIT_V(n) asm volatile("s_waitcnt vmcnt(" #n ")" ::: "memory")
; #define PG8_WAIT_L(n) asm volatile("s_waitcnt lgkmcnt(" #n ")" ::: "memory")
; #define PG8_BAR __builtin_amdgcn_s_barrier()
; #define PG8_SCHED __builtin_amdgcn_sched_barrier(0)
; template <class Epi, class Sched, bool ALIGN_EPI = false, bool SP2 = false, bool TWOA = false, bool AGM = false>
; __device__ __forceinline__ void gemm_phase(LAS unsigned char* lds, const Gemm g, const Sched& S, const Epi& E, int wid) {
;     ...
;         for (int t = 0; t < nt; t += 2) {
;             const bool last = (t == nt - 2);
;     ...
;             PG8_LDB(B0, 1, 0); PG8_LDB(B1, 1, 1); PG8_SCHED; PG8_LDA(At, 1, 0); PG8_STAGE(PG8_SA(0, 1), a2 + hstepA, voffA);
;             PG8_WAIT_V(8); PG8_WAIT_L(0); PG8_BAR; PG8_MMA(0, 0, At, B0); PG8_MMA(0, 1, At, B1); PG8_BAR; PG8_SCHED;
;             PG8_LDA(At, 1, 1); PG8_STAGE(PG8_SB(1, 0), b3, voffB); PG8_STAGE(PG8_SB(1, 1), b3 + hstep, voffB); PG8_STAGE(PG8_SA(1, 0), a3, voffA);
;             PG8_WAIT_V(8); PG8_WAIT_L(0); PG8_BAR; PG8_MMA(1, 0, At, B0); PG8_MMA(1, 1, At, B1); PG8_BAR; PG8_SCHED;
	s_add_i32 s68, 0, 0x18000
	v_add_u32_e32 v136, s68, v153
	s_add_i32 s69, 0, 0x1c000
	ds_read_b128 v[146:149], v136
	ds_read_b128 v[158:161], v136 offset:1024
	ds_read_b128 v[162:165], v136 offset:2048
	ds_read_b128 v[166:169], v136 offset:3072
	v_add_u32_e32 v136, s69, v153
	ds_read_b128 v[170:173], v136
	ds_read_b128 v[174:177], v136 offset:1024
	ds_read_b128 v[178:181], v136 offset:2048
	ds_read_b128 v[182:185], v136 offset:3072
	s_add_u32 s40, s40, 0x100000
	s_addc_u32 s41, s41, 0
	s_mov_b32 m0, s48
	ds_read_b128 v[186:189], v157 offset:32768
	ds_read_b128 v[190:193], v157 offset:33792
	ds_read_b128 v[194:197], v157 offset:34816
	ds_read_b128 v[198:201], v157 offset:35840
	ds_read_b128 v[202:205], v157 offset:36864
	ds_read_b128 v[206:209], v157 offset:37888
	ds_read_b128 v[210:213], v157 offset:38912
	ds_read_b128 v[214:217], v157 offset:39936
	global_load_lds_dwordx4 v134, s[40:41]
	s_mov_b32 m0, s49
	s_nop 0
	global_load_lds_dwordx4 v130, s[40:41]
	s_waitcnt vmcnt(8)
	s_waitcnt lgkmcnt(0)
	s_barrier
	s_setprio 1
	s_waitcnt lgkmcnt(0)
	v_mfma_f32_16x16x32_bf16 v[124:127], v[146:149], v[186:189], v[124:127]
	v_mfma_f32_16x16x32_bf16 v[120:123], v[162:165], v[186:189], v[120:123]
	v_mfma_f32_16x16x32_bf16 v[116:119], v[146:149], v[194:197], v[116:119]
	v_mfma_f32_16x16x32_bf16 v[108:111], v[162:165], v[194:197], v[108:111]
	v_mfma_f32_16x16x32_bf16 v[100:103], v[146:149], v[202:205], v[100:103]
	v_mfma_f32_16x16x32_bf16 v[92:95], v[162:165], v[202:205], v[92:95]
	v_mfma_f32_16x16x32_bf16 v[84:87], v[146:149], v[210:213], v[84:87]
	v_mfma_f32_16x16x32_bf16 v[76:79], v[162:165], v[210:213], v[76:79]
	v_mfma_f32_16x16x32_bf16 v[124:127], v[158:161], v[190:193], v[124:127]
	v_mfma_f32_16x16x32_bf16 v[120:123], v[166:169], v[190:193], v[120:123]
	v_mfma_f32_16x16x32_bf16 v[116:119], v[158:161], v[198:201], v[116:119]
	v_mfma_f32_16x16x32_bf16 v[108:111], v[166:169], v[198:201], v[108:111]
	v_mfma_f32_16x16x32_bf16 v[100:103], v[158:161], v[206:209], v[100:103]
	v_mfma_f32_16x16x32_bf16 v[92:95], v[166:169], v[206:209], v[92:95]
	v_mfma_f32_16x16x32_bf16 v[84:87], v[158:161], v[214:217], v[84:87]
	v_mfma_f32_16x16x32_bf16 v[76:79], v[166:169], v[214:217], v[76:79]
	s_setprio 0
	s_setprio 1
	v_mfma_f32_16x16x32_bf16 v[112:115], v[170:173], v[186:189], v[112:115]
	v_mfma_f32_16x16x32_bf16 v[104:107], v[178:181], v[186:189], v[104:107]
	v_mfma_f32_16x16x32_bf16 v[96:99], v[170:173], v[194:197], v[96:99]
	v_mfma_f32_16x16x32_bf16 v[88:91], v[178:181], v[194:197], v[88:91]
	v_mfma_f32_16x16x32_bf16 v[80:83], v[170:173], v[202:205], v[80:83]
	v_mfma_f32_16x16x32_bf16 v[72:75], v[178:181], v[202:205], v[72:75]
	v_mfma_f32_16x16x32_bf16 v[68:71], v[170:173], v[210:213], v[68:71]
	v_mfma_f32_16x16x32_bf16 v[64:67], v[178:181], v[210:213], v[64:67]
	v_mfma_f32_16x16x32_bf16 v[112:115], v[174:177], v[190:193], v[112:115]
	v_mfma_f32_16x16x32_bf16 v[104:107], v[182:185], v[190:193], v[104:107]
	v_mfma_f32_16x16x32_bf16 v[96:99], v[174:177], v[198:201], v[96:99]
	v_mfma_f32_16x16x32_bf16 v[88:91], v[182:185], v[198:201], v[88:91]
	v_mfma_f32_16x16x32_bf16 v[80:83], v[174:177], v[206:209], v[80:83]
	v_mfma_f32_16x16x32_bf16 v[72:75], v[182:185], v[206:209], v[72:75]
	v_mfma_f32_16x16x32_bf16 v[68:71], v[174:177], v[214:217], v[68:71]
	v_mfma_f32_16x16x32_bf16 v[64:67], v[182:185], v[214:217], v[64:67]
	s_setprio 0
	s_barrier
	s_add_i32 s40, s68, s44
	s_mov_b32 m0, s40
	ds_read_b128 v[186:189], v157 offset:49152
	ds_read_b128 v[190:193], v157 offset:50176
	ds_read_b128 v[194:197], v157 offset:51200
	ds_read_b128 v[198:201], v157 offset:52224
	ds_read_b128 v[202:205], v157 offset:53248
	ds_read_b128 v[206:209], v157 offset:54272
	ds_read_b128 v[210:213], v157 offset:55296
	ds_read_b128 v[214:217], v157 offset:56320
	global_load_lds_dwordx4 v132, s[98:99]
	s_add_i32 m0, s40, 0x2000
	s_add_u32 s38, s38, 0x100080
	s_addc_u32 s39, s39, 0
	s_add_i32 s40, s69, s44
	global_load_lds_dwordx4 v128, s[98:99]
	s_mov_b32 m0, s40
	s_nop 0
	global_load_lds_dwordx4 v132, s[38:39]
	s_add_i32 m0, s40, 0x2000
	s_nop 0
	global_load_lds_dwordx4 v128, s[38:39]
	s_mov_b32 m0, s52
	s_nop 0
	global_load_lds_dwordx4 v134, s[100:101]
	s_mov_b32 m0, s53
	s_nop 0
	global_load_lds_dwordx4 v130, s[100:101]
	s_waitcnt vmcnt(8)
	s_waitcnt lgkmcnt(0)
	s_barrier
	s_setprio 1
	s_waitcnt lgkmcnt(0)
	v_mfma_f32_16x16x32_bf16 v[60:63], v[146:149], v[186:189], v[60:63]
	v_mfma_f32_16x16x32_bf16 v[56:59], v[162:165], v[186:189], v[56:59]
	v_mfma_f32_16x16x32_bf16 v[52:55], v[146:149], v[194:197], v[52:55]
	v_mfma_f32_16x16x32_bf16 v[44:47], v[162:165], v[194:197], v[44:47]
	v_mfma_f32_16x16x32_bf16 v[36:39], v[146:149], v[202:205], v[36:39]
	v_mfma_f32_16x16x32_bf16 v[28:31], v[162:165], v[202:205], v[28:31]
	v_mfma_f32_16x16x32_bf16 v[20:23], v[146:149], v[210:213], v[20:23]
	v_mfma_f32_16x16x32_bf16 v[12:15], v[162:165], v[210:213], v[12:15]
	v_mfma_f32_16x16x32_bf16 v[60:63], v[158:161], v[190:193], v[60:63]
	v_mfma_f32_16x16x32_bf16 v[56:59], v[166:169], v[190:193], v[56:59]
	v_mfma_f32_16x16x32_bf16 v[52:55], v[158:161], v[198:201], v[52:55]
	v_mfma_f32_16x16x32_bf16 v[44:47], v[166:169], v[198:201], v[44:47]
	v_mfma_f32_16x16x32_bf16 v[36:39], v[158:161], v[206:209], v[36:39]
	v_mfma_f32_16x16x32_bf16 v[28:31], v[166:169], v[206:209], v[28:31]
	v_mfma_f32_16x16x32_bf16 v[20:23], v[158:161], v[214:217], v[20:23]
	v_mfma_f32_16x16x32_bf16 v[12:15], v[166:169], v[214:217], v[12:15]
	s_setprio 0
	s_setprio 1
	v_mfma_f32_16x16x32_bf16 v[48:51], v[170:173], v[186:189], v[48:51]
	v_mfma_f32_16x16x32_bf16 v[40:43], v[178:181], v[186:189], v[40:43]
	v_mfma_f32_16x16x32_bf16 v[32:35], v[170:173], v[194:197], v[32:35]
	v_mfma_f32_16x16x32_bf16 v[24:27], v[178:181], v[194:197], v[24:27]
	v_mfma_f32_16x16x32_bf16 v[16:19], v[170:173], v[202:205], v[16:19]
	v_mfma_f32_16x16x32_bf16 v[8:11], v[178:181], v[202:205], v[8:11]
	v_mfma_f32_16x16x32_bf16 v[4:7], v[170:173], v[210:213], v[4:7]
	v_mfma_f32_16x16x32_bf16 v[0:3], v[178:181], v[210:213], v[0:3]
	v_mfma_f32_16x16x32_bf16 v[48:51], v[174:177], v[190:193], v[48:51]
	v_mfma_f32_16x16x32_bf16 v[40:43], v[182:185], v[190:193], v[40:43]
	v_mfma_f32_16x16x32_bf16 v[32:35], v[174:177], v[198:201], v[32:35]
	v_mfma_f32_16x16x32_bf16 v[24:27], v[182:185], v[198:201], v[24:27]
	v_mfma_f32_16x16x32_bf16 v[16:19], v[174:177], v[206:209], v[16:19]
	v_mfma_f32_16x16x32_bf16 v[8:11], v[182:185], v[206:209], v[8:11]
	v_mfma_f32_16x16x32_bf16 v[4:7], v[174:177], v[214:217], v[4:7]
	v_mfma_f32_16x16x32_bf16 v[0:3], v[182:185], v[214:217], v[0:3]
	s_setprio 0
	s_barrier
	s_add_i32 s67, s67, 2
	s_add_u32 s36, s36, 0x100
	s_addc_u32 s37, s37, 0
	s_add_u32 s65, s65, 0x100
	s_addc_u32 s66, s66, 0
	s_cmp_gt_u32 s67, 61
	s_cbranch_scc0 .LBB0_901
	s_and_b64 vcc, exec, s[8:9]
	s_cbranch_vccz .LBB0_904
	s_barrier
